# attention A loop: first two PV MFMAs after the barrier issue bare, their VALU spread over the next six gaps
# speedup vs baseline: 1.0098x; 1.0098x over previous
; #define FA_SB() __builtin_amdgcn_sched_barrier(0)
; __device__ __forceinline__ void attn_unit_a(FLAS unsigned char* lds, const Unit u) {
;     ...
;         FA_PVM(0); pC0[0] = fadd_s(pC0[0], off); pC1[0] = fadd_s(pC1[0], off); pC0[1] = fadd_s(pC0[1], off); pC1[1] = fadd_s(pC1[1], off); pC0[2] = fadd_s(pC0[2], off); pC1[2] = fadd_s(pC1[2], off); FA_SB();
;         FA_PVM(1); ra = __builtin_fmaxf(__builtin_fmaxf(pC0[0], pC0[1]), pC0[2]); rb = __builtin_fmaxf(__builtin_fmaxf(pC1[0], pC1[1]), pC1[2]); pC0[3] = fadd_s(pC0[3], off); pC1[3] = fadd_s(pC1[3], off); pC0[4] = fadd_s(pC0[4], off); pC1[4] = fadd_s(pC1[4], off); FA_SB();
;         FA_PVM(2); ra = __builtin_fmaxf(__builtin_fmaxf(ra, pC0[3]), pC0[4]); rb = __builtin_fmaxf(__builtin_fmaxf(rb, pC1[3]), pC1[4]); pC0[5] = fadd_s(pC0[5], off); pC1[5] = fadd_s(pC1[5], off); pC0[6] = fadd_s(pC0[6], off); pC1[6] = fadd_s(pC1[6], off); FA_SB();
;         FA_PVM(3); ra = __builtin_fmaxf(__builtin_fmaxf(ra, pC0[5]), pC0[6]); rb = __builtin_fmaxf(__builtin_fmaxf(rb, pC1[5]), pC1[6]); pC0[7] = fadd_s(pC0[7], off); pC1[7] = fadd_s(pC1[7], off); pC0[8] = fadd_s(pC0[8], off); pC1[8] = fadd_s(pC1[8], off); FA_SB();
;         FA_PVM(4); ra = __builtin_fmaxf(__builtin_fmaxf(ra, pC0[7]), pC0[8]); rb = __builtin_fmaxf(__builtin_fmaxf(rb, pC1[7]), pC1[8]); pC0[9] = fadd_s(pC0[9], off); pC1[9] = fadd_s(pC1[9], off); pC0[10] = fadd_s(pC0[10], off); pC1[10] = fadd_s(pC1[10], off); FA_SB();
;         FA_PVM(5); ra = __builtin_fmaxf(__builtin_fmaxf(ra, pC0[9]), pC0[10]); rb = __builtin_fmaxf(__builtin_fmaxf(rb, pC1[9]), pC1[10]); pC0[11] = fadd_s(pC0[11], off); pC1[11] = fadd_s(pC1[11], off); pC0[12] = fadd_s(pC0[12], off); pC1[12] = fadd_s(pC1[12], off); FA_SB();
;         FA_PVM(6); ra = __builtin_fmaxf(__builtin_fmaxf(ra, pC0[11]), pC0[12]); rb = __builtin_fmaxf(__builtin_fmaxf(rb, pC1[11]), pC1[12]); pC0[13] = fadd_s(pC0[13], off); pC1[13] = fadd_s(pC1[13], off); pC0[14] = fadd_s(pC0[14], off); pC1[14] = fadd_s(pC1[14], off); FA_SB();
;         FA_PVM(7); ra = __builtin_fmaxf(__builtin_fmaxf(ra, pC0[13]), pC0[14]); rb = __builtin_fmaxf(__builtin_fmaxf(rb, pC1[13]), pC1[14]); pC0[15] = fadd_s(pC0[15], off); pC1[15] = fadd_s(pC1[15], off); ra = __builtin_fmaxf(__builtin_fmaxf(ra, pC0[15]), pC1[15]); rm = __builtin_fmaxf(ra, rb); FA_SB();
;         rm = xhalf_max(rm);
;         FA_SB();
;         if (first || __any(rm > 8.0f)) {
.LBB0_437:
	v_mfma_f32_32x32x16_bf16 v[32:47], v[132:135], v[204:207], v[32:47]
	ds_read_b128 v[132:135], v200 offset:16416
	s_waitcnt lgkmcnt(1)
	v_mfma_f32_32x32x16_bf16 v[16:31], v[136:139], v[204:207], v[16:31]
	ds_read_b128 v[136:139], v200 offset:21024
	v_max3_f32 v140, v96, v97, v98
	v_max3_f32 v141, v112, v113, v114
	v_cvt_pk_bf16_f32 v196, v72, v73
	v_cvt_pk_bf16_f32 v197, v74, v75
	v_add_f32_e32 v212, v80, v212
	v_add_f32_e32 v212, v81, v212
	v_max3_f32 v140, v140, v99, v100
	v_max3_f32 v141, v141, v115, v116
	v_mfma_f32_32x32x16_bf16 v[0:15], v[128:131], v[204:207], v[0:15]
	ds_read_b128 v[128:131], v200 offset:25632
	v_cvt_pk_bf16_f32 v198, v76, v77
	v_cvt_pk_bf16_f32 v199, v78, v79
	v_add_f32_e32 v212, v82, v212
	v_add_f32_e32 v212, v83, v212
	v_max3_f32 v140, v140, v101, v102
	v_max3_f32 v141, v141, v117, v118
	v_cvt_pk_bf16_f32 v192, v80, v81
	v_cvt_pk_bf16_f32 v193, v82, v83
	s_waitcnt lgkmcnt(1)
	v_mfma_f32_32x32x16_bf16 v[48:63], v[132:135], v[196:199], v[48:63]
	ds_read_b128 v[132:135], v200 offset:30240
	v_add_f32_e32 v212, v84, v212
	v_add_f32_e32 v212, v85, v212
	v_max3_f32 v140, v140, v103, v104
	v_max3_f32 v141, v141, v119, v120
	v_cvt_pk_bf16_f32 v194, v84, v85
	v_cvt_pk_bf16_f32 v195, v86, v87
	v_add_f32_e32 v212, v86, v212
	v_add_f32_e32 v212, v87, v212
	v_mfma_f32_32x32x16_bf16 v[32:47], v[136:139], v[196:199], v[32:47]
	ds_read_b128 v[136:139], v200 offset:16448
	v_max3_f32 v140, v140, v105, v106
	v_max3_f32 v141, v141, v121, v122
	v_cvt_pk_bf16_f32 v188, v88, v89
	v_cvt_pk_bf16_f32 v189, v90, v91
	v_add_f32_e32 v212, v88, v212
	v_add_f32_e32 v212, v89, v212
	v_max3_f32 v140, v140, v107, v108
	v_max3_f32 v141, v141, v123, v124
	s_waitcnt lgkmcnt(1)
	v_mfma_f32_32x32x16_bf16 v[16:31], v[128:131], v[196:199], v[16:31]
	ds_read_b128 v[128:131], v200 offset:21056
	v_cvt_pk_bf16_f32 v190, v92, v93
	v_cvt_pk_bf16_f32 v191, v94, v95
	v_add_f32_e32 v212, v90, v212
	v_add_f32_e32 v212, v91, v212
	v_max3_f32 v140, v140, v109, v110
	v_max3_f32 v141, v141, v125, v126
	v_add_f32_e32 v212, v92, v212
	v_add_f32_e32 v212, v93, v212
	v_mfma_f32_32x32x16_bf16 v[0:15], v[132:135], v[196:199], v[0:15]
	ds_read_b128 v[132:135], v200 offset:25664
	v_max3_f32 v140, v140, v141, v111
	v_max_f32_e32 v140, v140, v127
	v_add_f32_e32 v212, v94, v212
	v_add_f32_e32 v212, v95, v212
	s_andn2_b64 vcc, exec, s[20:21]
	s_cbranch_vccnz .LBB0_440
	v_cmp_lt_f32_e32 vcc, s39, v140
	s_cbranch_vccnz .Lresc_e
	s_mov_b64 s[20:21], 0

; #define FA_SB() __builtin_amdgcn_sched_barrier(0)
; __device__ __forceinline__ void attn_unit_a(FLAS unsigned char* lds, const Unit u) {
;     ...
;         FA_PVM(0); pC0[0] = fadd_s(pC0[0], off); pC1[0] = fadd_s(pC1[0], off); pC0[1] = fadd_s(pC0[1], off); pC1[1] = fadd_s(pC1[1], off); pC0[2] = fadd_s(pC0[2], off); pC1[2] = fadd_s(pC1[2], off); FA_SB();
;         FA_PVM(1); ra = __builtin_fmaxf(__builtin_fmaxf(pC0[0], pC0[1]), pC0[2]); rb = __builtin_fmaxf(__builtin_fmaxf(pC1[0], pC1[1]), pC1[2]); pC0[3] = fadd_s(pC0[3], off); pC1[3] = fadd_s(pC1[3], off); pC0[4] = fadd_s(pC0[4], off); pC1[4] = fadd_s(pC1[4], off); FA_SB();
;         FA_PVM(2); ra = __builtin_fmaxf(__builtin_fmaxf(ra, pC0[3]), pC0[4]); rb = __builtin_fmaxf(__builtin_fmaxf(rb, pC1[3]), pC1[4]); pC0[5] = fadd_s(pC0[5], off); pC1[5] = fadd_s(pC1[5], off); pC0[6] = fadd_s(pC0[6], off); pC1[6] = fadd_s(pC1[6], off); FA_SB();
;         FA_PVM(3); ra = __builtin_fmaxf(__builtin_fmaxf(ra, pC0[5]), pC0[6]); rb = __builtin_fmaxf(__builtin_fmaxf(rb, pC1[5]), pC1[6]); pC0[7] = fadd_s(pC0[7], off); pC1[7] = fadd_s(pC1[7], off); pC0[8] = fadd_s(pC0[8], off); pC1[8] = fadd_s(pC1[8], off); FA_SB();
;         FA_PVM(4); ra = __builtin_fmaxf(__builtin_fmaxf(ra, pC0[7]), pC0[8]); rb = __builtin_fmaxf(__builtin_fmaxf(rb, pC1[7]), pC1[8]); pC0[9] = fadd_s(pC0[9], off); pC1[9] = fadd_s(pC1[9], off); pC0[10] = fadd_s(pC0[10], off); pC1[10] = fadd_s(pC1[10], off); FA_SB();
;         FA_PVM(5); ra = __builtin_fmaxf(__builtin_fmaxf(ra, pC0[9]), pC0[10]); rb = __builtin_fmaxf(__builtin_fmaxf(rb, pC1[9]), pC1[10]); pC0[11] = fadd_s(pC0[11], off); pC1[11] = fadd_s(pC1[11], off); pC0[12] = fadd_s(pC0[12], off); pC1[12] = fadd_s(pC1[12], off); FA_SB();
;         FA_PVM(6); ra = __builtin_fmaxf(__builtin_fmaxf(ra, pC0[11]), pC0[12]); rb = __builtin_fmaxf(__builtin_fmaxf(rb, pC1[11]), pC1[12]); pC0[13] = fadd_s(pC0[13], off); pC1[13] = fadd_s(pC1[13], off); pC0[14] = fadd_s(pC0[14], off); pC1[14] = fadd_s(pC1[14], off); FA_SB();
;         FA_PVM(7); ra = __builtin_fmaxf(__builtin_fmaxf(ra, pC0[13]), pC0[14]); rb = __builtin_fmaxf(__builtin_fmaxf(rb, pC1[13]), pC1[14]); pC0[15] = fadd_s(pC0[15], off); pC1[15] = fadd_s(pC1[15], off); ra = __builtin_fmaxf(__builtin_fmaxf(ra, pC0[15]), pC1[15]); rm = __builtin_fmaxf(ra, rb); FA_SB();
;         rm = xhalf_max(rm);
;         FA_SB();
;         if (first || __any(rm > 8.0f)) {
.LBB0_460:
	v_mfma_f32_32x32x16_bf16 v[32:47], v[132:135], v[140:143], v[32:47]
	ds_read_b128 v[132:135], v201 offset:16416
	s_waitcnt lgkmcnt(1)
	v_mfma_f32_32x32x16_bf16 v[16:31], v[136:139], v[140:143], v[16:31]
	ds_read_b128 v[136:139], v201 offset:21024
	v_max3_f32 v96, v64, v65, v66
	v_max3_f32 v97, v80, v81, v82
	v_cvt_pk_bf16_f32 v232, v104, v105
	v_cvt_pk_bf16_f32 v233, v106, v107
	v_add_f32_e32 v212, v112, v212
	v_add_f32_e32 v212, v113, v212
	v_max3_f32 v96, v96, v67, v68
	v_mfma_f32_32x32x16_bf16 v[0:15], v[128:131], v[140:143], v[0:15]
	ds_read_b128 v[128:131], v201 offset:25632
	v_max3_f32 v97, v97, v83, v84
	v_cvt_pk_bf16_f32 v234, v108, v109
	v_cvt_pk_bf16_f32 v235, v110, v111
	v_add_f32_e32 v212, v114, v212
	v_add_f32_e32 v212, v115, v212
	v_max3_f32 v96, v96, v69, v70
	v_max3_f32 v97, v97, v85, v86
	s_waitcnt lgkmcnt(1)
	v_mfma_f32_32x32x16_bf16 v[48:63], v[132:135], v[232:235], v[48:63]
	ds_read_b128 v[132:135], v201 offset:30240
	v_add_f32_e32 v212, v116, v212
	v_add_f32_e32 v212, v117, v212
	v_max3_f32 v96, v96, v71, v72
	v_max3_f32 v97, v97, v87, v88
	v_add_f32_e32 v212, v118, v212
	v_add_f32_e32 v212, v119, v212
	v_max3_f32 v96, v96, v73, v74
	v_mfma_f32_32x32x16_bf16 v[32:47], v[136:139], v[232:235], v[32:47]
	ds_read_b128 v[136:139], v201 offset:16448
	v_max3_f32 v97, v97, v89, v90
	v_cvt_pk_bf16_f32 v140, v112, v113
	v_cvt_pk_bf16_f32 v141, v114, v115
	v_add_f32_e32 v212, v120, v212
	v_add_f32_e32 v212, v121, v212
	v_max3_f32 v96, v96, v75, v76
	v_max3_f32 v97, v97, v91, v92
	s_waitcnt lgkmcnt(1)
	v_mfma_f32_32x32x16_bf16 v[16:31], v[128:131], v[232:235], v[16:31]
	ds_read_b128 v[128:131], v201 offset:21056
	v_cvt_pk_bf16_f32 v142, v116, v117
	v_cvt_pk_bf16_f32 v143, v118, v119
	v_add_f32_e32 v212, v122, v212
	v_add_f32_e32 v212, v123, v212
	v_max3_f32 v96, v96, v77, v78
	v_max3_f32 v97, v97, v93, v94
	v_add_f32_e32 v212, v124, v212
	v_mfma_f32_32x32x16_bf16 v[0:15], v[132:135], v[232:235], v[0:15]
	ds_read_b128 v[132:135], v201 offset:25664
	v_add_f32_e32 v212, v125, v212
	v_max3_f32 v96, v96, v97, v79
	v_max_f32_e32 v96, v96, v95
	v_add_f32_e32 v212, v126, v212
	v_add_f32_e32 v212, v127, v212
	v_cmp_lt_f32_e32 vcc, s39, v96
	s_mov_b64 s[0:1], 0
	s_cbranch_vccnz .Lresc_o
